# v7_desync500
# speedup vs baseline: 1.0040x; 1.0002x over previous
; __device__ __forceinline__ void gemm_phase(const Params& P, const GArgs& ga, int wid_s, int first, int stride) {
;   const int nN = ga.N / BM;
;   const int nM = ga.split ? NP / BM : NTOK / BM;
;   const int nwg = nM * nN;
;   const int nitems = ga.split ? nwg + (NS / BM) * nN * 8 : nwg;
;   const int nkt_all = ga.K / BK;
;   for (int t = first; t < nitems; t += stride) {
.LBB0_288:
	s_and_b64 s[8:9], s[4:5], exec
	s_cselect_b32 s41, 0x44, 64
	s_mul_i32 s54, s78, s41
	s_lshl_b32 s8, s78, 5
	s_add_i32 s8, s54, s8
	s_and_b64 s[4:5], s[4:5], exec
	s_cselect_b32 s91, s54, s8
	s_cmp_ge_i32 s59, s91
	s_cbranch_scc1 .LBB0_261
	v_cvt_f32_u32_e32 v0, s78
	s_lshl_b32 s44, s78, 2
	v_cvt_f32_u32_e32 v2, s44
	s_xor_b64 s[34:35], s[0:1], -1
	v_rcp_iflag_f32_e32 v0, v0
	s_sub_i32 s0, 0, s78
	v_rcp_iflag_f32_e32 v2, v2
	s_mov_b64 s[36:37], s[84:85]
	v_mul_f32_e32 v0, 0x4f7ffffe, v0
	v_cvt_u32_f32_e32 v0, v0
	s_xor_b64 s[96:97], s[6:7], -1
	s_lshr_b32 s76, s93, 6
	s_lshr_b32 s42, s93, 9
	v_readfirstlane_b32 s1, v0
	v_mul_f32_e32 v0, 0x4f7ffffe, v2
	v_cvt_u32_f32_e32 v0, v0
	s_mul_i32 s0, s0, s1
	s_mul_hi_u32 s0, s1, s0
	s_add_i32 s45, s1, s0
	s_sub_i32 s0, 0, s44
	v_readfirstlane_b32 s1, v0
	s_mul_i32 s0, s0, s1
	s_mul_hi_u32 s0, s1, s0
	s_lshr_b32 s43, s54, 3
	s_mov_b32 s21, s20
	s_add_i32 s46, s1, s0
	s_lshl_b32 s47, s93, 7
	s_lshl_b32 s48, s93, 1
	s_lshl_b32 s49, s93, 9
	s_bitcmp1_b32 s59, 3
	s_cbranch_scc0 .Ldsy_skip
	s_memrealtime s[0:1]
	s_waitcnt lgkmcnt(0)
	s_add_u32 s0, s0, 500
	s_addc_u32 s1, s1, 0
.Ldsy_spin:
	s_memrealtime s[4:5]
	s_waitcnt lgkmcnt(0)
	s_sub_u32 s4, s4, s0
	s_subb_u32 s5, s5, s1
	s_cmp_lt_i32 s5, 0
	s_cbranch_scc1 .Ldsy_spin
.Ldsy_skip:
	s_branch .LBB0_291
.LBB0_290:
	s_add_i32 s59, s59, s39
	s_cmp_lt_i32 s59, s91
	s_cbranch_scc1 .Lnt_back
	s_waitcnt vmcnt(0)
	s_barrier
	s_branch .LBB0_260
